# v69 + nt on the phase-0 write-through stores (XH / W1T / weight transposes)
# speedup vs baseline: 1.0025x; 1.0025x over previous
.LBB0_11:
	s_or_b64 exec, exec, s[8:9]
	s_waitcnt vmcnt(0)
	ds_write2_b32 v46, v4, v5 offset1:1
	ds_write2_b32 v46, v6, v7 offset0:2 offset1:3
	v_add_u32_e32 v4, 0x420, v46
	ds_write2_b32 v4, v0, v1 offset1:1
	v_add_u32_e32 v0, 0x428, v46
	ds_write2_b32 v0, v2, v3 offset1:1
	v_add_u32_e32 v0, 0x840, v46
	ds_write2_b32 v0, v12, v13 offset1:1
	v_add_u32_e32 v0, 0x848, v46
	ds_write2_b32 v0, v14, v15 offset1:1
	v_add_u32_e32 v0, 0xc60, v46
	ds_write2_b32 v0, v8, v9 offset1:1
	v_add_u32_e32 v0, 0xc68, v46
	ds_write2_b32 v0, v10, v11 offset1:1
	v_add_u32_e32 v0, 0x1080, v46
	ds_write2_b32 v0, v20, v21 offset1:1
	v_add_u32_e32 v0, 0x1088, v46
	ds_write2_b32 v0, v22, v23 offset1:1
	v_add_u32_e32 v0, 0x14a0, v46
	ds_write2_b32 v0, v16, v17 offset1:1
	v_add_u32_e32 v0, 0x14a8, v46
	ds_write2_b32 v0, v18, v19 offset1:1
	v_add_u32_e32 v0, 0x18c0, v46
	ds_write2_b32 v0, v28, v29 offset1:1
	v_add_u32_e32 v0, 0x18c8, v46
	ds_write2_b32 v0, v30, v31 offset1:1
	v_add_u32_e32 v0, 0x1ce0, v46
	ds_write2_b32 v0, v24, v25 offset1:1
	v_add_u32_e32 v0, 0x1ce8, v46
	ds_write2_b32 v0, v26, v27 offset1:1
	s_waitcnt lgkmcnt(0)
	ds_read2_b32 v[0:1], v45 offset0:198 offset1:231
	ds_read2_b32 v[4:5], v45 offset0:132 offset1:165
	ds_read2_b32 v[6:7], v45 offset0:66 offset1:99
	ds_read2_b32 v[8:9], v45 offset1:33
	s_ashr_i32 s7, s6, 31
	v_lshl_add_u64 v[10:11], s[6:7], 1, v[36:37]
	s_waitcnt lgkmcnt(2)
	v_cvt_pk_f16_f32 v2, v4, v5
	v_add_u32_e32 v4, s33, v44
	v_ashrrev_i32_e32 v5, 31, v4
	v_cvt_pk_f16_f32 v3, v0, v1
	s_waitcnt lgkmcnt(1)
	v_cvt_pk_f16_f32 v1, v6, v7
	v_lshlrev_b64 v[6:7], 11, v[4:5]
	s_waitcnt lgkmcnt(0)
	v_cvt_pk_f16_f32 v0, v8, v9
	v_lshl_add_u64 v[6:7], v[10:11], 0, v[6:7]
	global_store_dwordx4 v[6:7], v[0:3], off sc1 nt
	s_nop 1
	ds_read2_b32 v[0:1], v45 offset0:206 offset1:239
	ds_read2_b32 v[6:7], v45 offset0:140 offset1:173
	ds_read2_b32 v[8:9], v45 offset0:74 offset1:107
	ds_read2_b32 v[12:13], v45 offset0:8 offset1:41
	s_add_i32 s15, s15, s10
	s_waitcnt lgkmcnt(3)
	v_cvt_pk_f16_f32 v3, v0, v1
	s_waitcnt lgkmcnt(2)
	v_cvt_pk_f16_f32 v2, v6, v7
	v_add_u32_e32 v6, 8, v4
	v_ashrrev_i32_e32 v7, 31, v6
	v_lshlrev_b64 v[6:7], 11, v[6:7]
	s_waitcnt lgkmcnt(1)
	v_cvt_pk_f16_f32 v1, v8, v9
	s_waitcnt lgkmcnt(0)
	v_cvt_pk_f16_f32 v0, v12, v13
	v_lshl_add_u64 v[6:7], v[10:11], 0, v[6:7]
	global_store_dwordx4 v[6:7], v[0:3], off sc1 nt
	s_nop 1
	ds_read2_b32 v[0:1], v45 offset0:214 offset1:247
	ds_read2_b32 v[6:7], v45 offset0:148 offset1:181
	ds_read2_b32 v[8:9], v45 offset0:82 offset1:115
	ds_read2_b32 v[12:13], v45 offset0:16 offset1:49
	s_add_i32 s11, s11, s12
	s_waitcnt lgkmcnt(3)
	v_cvt_pk_f16_f32 v3, v0, v1
	s_waitcnt lgkmcnt(2)
	v_cvt_pk_f16_f32 v2, v6, v7
	v_add_u32_e32 v6, 16, v4
	v_ashrrev_i32_e32 v7, 31, v6
	v_lshlrev_b64 v[6:7], 11, v[6:7]
	s_waitcnt lgkmcnt(1)
	v_cvt_pk_f16_f32 v1, v8, v9
	s_waitcnt lgkmcnt(0)
	v_cvt_pk_f16_f32 v0, v12, v13
	v_lshl_add_u64 v[6:7], v[10:11], 0, v[6:7]
	global_store_dwordx4 v[6:7], v[0:3], off sc1 nt
	s_nop 1
	ds_read2_b32 v[0:1], v45 offset0:222 offset1:255
	ds_read2_b32 v[6:7], v45 offset0:156 offset1:189
	ds_read2_b32 v[8:9], v45 offset0:90 offset1:123
	ds_read2_b32 v[12:13], v45 offset0:24 offset1:57
	v_add_u32_e32 v4, 24, v4
	v_ashrrev_i32_e32 v5, 31, v4
	v_lshlrev_b64 v[4:5], 11, v[4:5]
	s_waitcnt lgkmcnt(3)
	v_cvt_pk_f16_f32 v3, v0, v1
	s_waitcnt lgkmcnt(2)
	v_cvt_pk_f16_f32 v2, v6, v7
	s_waitcnt lgkmcnt(1)
	v_cvt_pk_f16_f32 v1, v8, v9
	s_waitcnt lgkmcnt(0)
	v_cvt_pk_f16_f32 v0, v12, v13
	v_lshl_add_u64 v[4:5], v[10:11], 0, v[4:5]
	global_store_dwordx4 v[4:5], v[0:3], off sc1 nt
	s_nop 1
	s_waitcnt lgkmcnt(0)
	s_cmpk_gt_i32 s15, 0x147f
	s_cbranch_scc1 .LBB0_48

.LBB0_53:
	s_or_b64 exec, exec, s[0:1]
	v_pk_mul_f32 v[4:5], v[60:61], v[0:1] op_sel_hi:[1,0]
	v_pk_mul_f32 v[6:7], v[62:63], v[0:1] op_sel_hi:[1,0]
	v_lshl_add_u64 v[2:3], v[66:67], 0, s[50:51]
	v_cvt_pk_f16_f32 v7, v6, v7
	v_cvt_pk_f16_f32 v6, v4, v5
	global_store_dwordx2 v[2:3], v[6:7], off sc1 nt
	s_nop 1
	v_pk_mul_f32 v[4:5], v[56:57], v[0:1] op_sel_hi:[1,0]
	v_pk_mul_f32 v[6:7], v[58:59], v[0:1] op_sel_hi:[1,0]
	v_lshl_add_u64 v[2:3], v[66:67], 0, s[80:81]
	v_cvt_pk_f16_f32 v7, v6, v7
	v_cvt_pk_f16_f32 v6, v4, v5
	global_store_dwordx2 v[2:3], v[6:7], off sc1 nt
	s_nop 1
	v_pk_mul_f32 v[4:5], v[48:49], v[0:1] op_sel_hi:[1,0]
	v_pk_mul_f32 v[6:7], v[50:51], v[0:1] op_sel_hi:[1,0]
	s_add_u32 s10, s10, s12
	v_lshl_add_u64 v[2:3], v[66:67], 0, s[82:83]
	v_cvt_pk_f16_f32 v7, v6, v7
	v_cvt_pk_f16_f32 v6, v4, v5
	global_store_dwordx2 v[2:3], v[6:7], off sc1 nt
	s_nop 1
	v_pk_mul_f32 v[4:5], v[44:45], v[0:1] op_sel_hi:[1,0]
	v_pk_mul_f32 v[0:1], v[46:47], v[0:1] op_sel_hi:[1,0]
	s_addc_u32 s11, s11, s13
	v_lshl_add_u64 v[2:3], v[66:67], 0, s[84:85]
	v_cvt_pk_f16_f32 v1, v0, v1
	v_cvt_pk_f16_f32 v0, v4, v5
	global_store_dwordx2 v[2:3], v[0:1], off sc1 nt
	s_nop 1
	s_add_u32 s14, s14, s16
	s_addc_u32 s15, s15, s17
	s_cmp_lt_i32 s10, 0x8100
	v_lshl_add_u64 v[64:65], v[64:65], 0, s[22:23]
	s_cbranch_scc0 .LBB0_70

.LBB0_64:
	s_or_b64 exec, exec, s[86:87]
	s_waitcnt lgkmcnt(2)
	v_add_f32_e32 v84, v66, v67
	v_lshl_add_u64 v[66:67], s[76:77], 0, v[64:65]
	s_mov_b64 s[0:1], 0x2800000
	v_pk_mul_f32 v[24:25], v[24:25], v[68:69] op_sel_hi:[1,0]
	v_pk_mul_f32 v[26:27], v[26:27], v[68:69] op_sel_hi:[1,0]
	v_lshl_add_u64 v[82:83], v[66:67], 0, s[0:1]
	v_cvt_pk_f16_f32 v27, v26, v27
	v_cvt_pk_f16_f32 v26, v24, v25
	global_store_dwordx2 v[82:83], v[26:27], off sc1 nt
	s_nop 1
	s_mov_b64 s[0:1], 0x2800200
	v_pk_mul_f32 v[16:17], v[16:17], v[68:69] op_sel_hi:[1,0]
	v_pk_mul_f32 v[18:19], v[18:19], v[68:69] op_sel_hi:[1,0]
	v_pk_mul_f32 v[4:5], v[4:5], v[68:69] op_sel_hi:[1,0]
	v_pk_mul_f32 v[6:7], v[6:7], v[68:69] op_sel_hi:[1,0]
	v_lshl_add_u64 v[24:25], v[66:67], 0, s[0:1]
	v_cvt_pk_f16_f32 v19, v18, v19
	v_cvt_pk_f16_f32 v18, v16, v17
	global_store_dwordx2 v[24:25], v[18:19], off sc1 nt
	s_nop 1
	s_mov_b64 s[0:1], 0x2800400
	v_pk_mul_f32 v[8:9], v[8:9], v[68:69] op_sel_hi:[1,0]
	v_pk_mul_f32 v[10:11], v[10:11], v[68:69] op_sel_hi:[1,0]
	v_cvt_pk_f16_f32 v7, v6, v7
	v_cvt_pk_f16_f32 v6, v4, v5
	v_fmamk_f32 v5, v84, 0x3a800000, v75
	v_lshl_add_u64 v[16:17], v[66:67], 0, s[0:1]
	v_cvt_pk_f16_f32 v11, v10, v11
	v_cvt_pk_f16_f32 v10, v8, v9
	global_store_dwordx2 v[16:17], v[10:11], off sc1 nt
	s_nop 1
	s_mov_b64 s[0:1], 0x2800600
	v_rsq_f32_e32 v4, v5
	v_lshl_add_u64 v[8:9], v[66:67], 0, s[0:1]
	global_store_dwordx2 v[8:9], v[6:7], off sc1 nt
	s_nop 1
	s_and_saveexec_b64 s[0:1], vcc
	s_cbranch_execz .LBB0_66
	v_mul_f32_e32 v5, v5, v4
	v_cndmask_b32_e64 v5, 0, v5, s[4:5]
	s_add_u32 s4, s76, s14
	s_addc_u32 s5, s77, s15
	global_store_dword v76, v5, s[4:5] offset:4
.LBB0_66:
	s_or_b64 exec, exec, s[0:1]
	v_pk_mul_f32 v[8:9], v[36:37], v[4:5] op_sel_hi:[1,0]
	v_pk_mul_f32 v[10:11], v[38:39], v[4:5] op_sel_hi:[1,0]
	s_mov_b64 s[0:1], 0x2800800
	v_cvt_pk_f16_f32 v11, v10, v11
	v_cvt_pk_f16_f32 v10, v8, v9
	v_lshl_add_u64 v[6:7], v[66:67], 0, s[0:1]
	global_store_dwordx2 v[6:7], v[10:11], off sc1 nt
	s_nop 1
	v_pk_mul_f32 v[8:9], v[28:29], v[4:5] op_sel_hi:[1,0]
	v_pk_mul_f32 v[10:11], v[30:31], v[4:5] op_sel_hi:[1,0]
	s_mov_b64 s[0:1], 0x2800a00
	v_cvt_pk_f16_f32 v11, v10, v11
	v_cvt_pk_f16_f32 v10, v8, v9
	v_lshl_add_u64 v[6:7], v[66:67], 0, s[0:1]
	global_store_dwordx2 v[6:7], v[10:11], off sc1 nt
	s_nop 1
	v_pk_mul_f32 v[8:9], v[20:21], v[4:5] op_sel_hi:[1,0]
	v_pk_mul_f32 v[10:11], v[22:23], v[4:5] op_sel_hi:[1,0]
	s_waitcnt lgkmcnt(1)
	v_add_f32_e32 v16, v80, v81
	s_mov_b64 s[0:1], 0x2800c00
	v_cvt_pk_f16_f32 v11, v10, v11
	v_cvt_pk_f16_f32 v10, v8, v9
	v_pk_mul_f32 v[8:9], v[12:13], v[4:5] op_sel_hi:[1,0]
	v_pk_mul_f32 v[4:5], v[14:15], v[4:5] op_sel_hi:[1,0]
	v_lshl_add_u64 v[6:7], v[66:67], 0, s[0:1]
	global_store_dwordx2 v[6:7], v[10:11], off sc1 nt
	s_nop 1
	v_cvt_pk_f16_f32 v11, v4, v5
	v_fmamk_f32 v5, v16, 0x3a800000, v75
	s_mov_b64 s[0:1], 0x2800e00
	v_rsq_f32_e32 v4, v5
	v_lshl_add_u64 v[6:7], v[66:67], 0, s[0:1]
	v_cvt_pk_f16_f32 v10, v8, v9
	global_store_dwordx2 v[6:7], v[10:11], off sc1 nt
	s_nop 1
	s_and_saveexec_b64 s[0:1], vcc
	s_cbranch_execz .LBB0_68
	v_mul_f32_e32 v5, v5, v4
	s_add_u32 s4, s76, s14
	v_cndmask_b32_e64 v5, 0, v5, s[6:7]
	s_addc_u32 s5, s77, s15
	global_store_dword v76, v5, s[4:5] offset:8
.LBB0_68:
	s_or_b64 exec, exec, s[0:1]
	s_waitcnt lgkmcnt(0)
	v_add_f32_e32 v5, v78, v79
	v_pk_mul_f32 v[8:9], v[52:53], v[4:5] op_sel_hi:[1,0]
	v_pk_mul_f32 v[10:11], v[54:55], v[4:5] op_sel_hi:[1,0]
	s_mov_b64 s[0:1], 0x2801000
	v_cvt_pk_f16_f32 v11, v10, v11
	v_cvt_pk_f16_f32 v10, v8, v9
	v_lshl_add_u64 v[6:7], v[66:67], 0, s[0:1]
	global_store_dwordx2 v[6:7], v[10:11], off sc1 nt
	s_nop 1
	v_pk_mul_f32 v[8:9], v[40:41], v[4:5] op_sel_hi:[1,0]
	v_pk_mul_f32 v[10:11], v[42:43], v[4:5] op_sel_hi:[1,0]
	s_mov_b64 s[0:1], 0x2801200
	v_cvt_pk_f16_f32 v11, v10, v11
	v_cvt_pk_f16_f32 v10, v8, v9
	v_pk_mul_f32 v[0:1], v[0:1], v[4:5] op_sel_hi:[1,0]
	v_pk_mul_f32 v[2:3], v[2:3], v[4:5] op_sel_hi:[1,0]
	v_lshl_add_u64 v[6:7], v[66:67], 0, s[0:1]
	global_store_dwordx2 v[6:7], v[10:11], off sc1 nt
	s_nop 1
	v_pk_mul_f32 v[8:9], v[32:33], v[4:5] op_sel_hi:[1,0]
	v_pk_mul_f32 v[10:11], v[34:35], v[4:5] op_sel_hi:[1,0]
	v_cvt_pk_f16_f32 v3, v2, v3
	v_cvt_pk_f16_f32 v2, v0, v1
	v_fmamk_f32 v1, v5, 0x3a800000, v75
	v_lshl_add_u64 v[6:7], v[66:67], 0, s[26:27]
	v_cvt_pk_f16_f32 v11, v10, v11
	v_cvt_pk_f16_f32 v10, v8, v9
	global_store_dwordx2 v[6:7], v[10:11], off sc1 nt
	s_nop 1
	v_rsq_f32_e32 v0, v1
	v_lshl_add_u64 v[6:7], v[66:67], 0, s[34:35]
	global_store_dwordx2 v[6:7], v[2:3], off sc1 nt
	s_nop 1
	s_and_saveexec_b64 s[0:1], vcc
	s_cbranch_execz .LBB0_53
	v_mul_f32_e32 v1, v1, v0
	s_add_u32 s4, s76, s14
	v_cndmask_b32_e64 v1, 0, v1, s[8:9]
	s_addc_u32 s5, s77, s15
	global_store_dword v76, v1, s[4:5] offset:12
	s_branch .LBB0_53

.LBB0_126:
	ds_write2_b32 v215, v0, v1 offset1:1
	ds_write2_b32 v215, v2, v3 offset0:2 offset1:3
	ds_write2_b32 v216, v4, v5 offset1:1
	ds_write2_b32 v217, v6, v7 offset1:1
	ds_write2_b32 v218, v8, v9 offset1:1
	ds_write2_b32 v219, v10, v11 offset1:1
	ds_write2_b32 v220, v12, v13 offset1:1
	ds_write2_b32 v221, v14, v15 offset1:1
	ds_write2_b32 v222, v16, v17 offset1:1
	ds_write2_b32 v223, v18, v19 offset1:1
	ds_write2_b32 v224, v20, v21 offset1:1
	ds_write2_b32 v225, v22, v23 offset1:1
	ds_write2_b32 v226, v24, v25 offset1:1
	ds_write2_b32 v227, v26, v27 offset1:1
	ds_write2_b32 v228, v28, v29 offset1:1
	ds_write2_b32 v229, v30, v31 offset1:1
	s_waitcnt lgkmcnt(0)
	ds_read2_b32 v[0:1], v214 offset0:198 offset1:231
	ds_read2_b32 v[4:5], v214 offset0:132 offset1:165
	ds_read2_b32 v[6:7], v214 offset0:66 offset1:99
	ds_read2_b32 v[8:9], v214 offset1:33
	s_sub_i32 s0, 0, s4
	s_add_i32 s0, s0, s12
	s_waitcnt lgkmcnt(2)
	v_cvt_pk_f16_f32 v2, v4, v5
	v_add_u32_e32 v4, s0, v210
	s_ashr_i32 s9, s8, 31
	v_ashrrev_i32_e32 v5, 31, v4
	v_lshl_add_u64 v[10:11], s[8:9], 1, v[204:205]
	v_cvt_pk_f16_f32 v3, v0, v1
	s_waitcnt lgkmcnt(1)
	v_cvt_pk_f16_f32 v1, v6, v7
	v_lshlrev_b64 v[6:7], 11, v[4:5]
	s_waitcnt lgkmcnt(0)
	v_cvt_pk_f16_f32 v0, v8, v9
	v_lshl_add_u64 v[6:7], v[10:11], 0, v[6:7]
	global_store_dwordx4 v[6:7], v[0:3], off sc1 nt
	s_nop 1
	ds_read2_b32 v[0:1], v214 offset0:206 offset1:239
	ds_read2_b32 v[6:7], v214 offset0:140 offset1:173
	ds_read2_b32 v[8:9], v214 offset0:74 offset1:107
	ds_read2_b32 v[12:13], v214 offset0:8 offset1:41
	s_waitcnt lgkmcnt(3)
	v_cvt_pk_f16_f32 v3, v0, v1
	s_waitcnt lgkmcnt(2)
	v_cvt_pk_f16_f32 v2, v6, v7
	v_add_u32_e32 v6, 8, v4
	v_ashrrev_i32_e32 v7, 31, v6
	v_lshlrev_b64 v[6:7], 11, v[6:7]
	s_waitcnt lgkmcnt(1)
	v_cvt_pk_f16_f32 v1, v8, v9
	s_waitcnt lgkmcnt(0)
	v_cvt_pk_f16_f32 v0, v12, v13
	v_lshl_add_u64 v[6:7], v[10:11], 0, v[6:7]
	global_store_dwordx4 v[6:7], v[0:3], off sc1 nt
	s_nop 1
	ds_read2_b32 v[0:1], v214 offset0:214 offset1:247
	ds_read2_b32 v[6:7], v214 offset0:148 offset1:181
	ds_read2_b32 v[8:9], v214 offset0:82 offset1:115
	ds_read2_b32 v[12:13], v214 offset0:16 offset1:49
	s_waitcnt lgkmcnt(3)
	v_cvt_pk_f16_f32 v3, v0, v1
	s_waitcnt lgkmcnt(2)
	v_cvt_pk_f16_f32 v2, v6, v7
	v_add_u32_e32 v6, 16, v4
	v_ashrrev_i32_e32 v7, 31, v6
	v_lshlrev_b64 v[6:7], 11, v[6:7]
	s_waitcnt lgkmcnt(1)
	v_cvt_pk_f16_f32 v1, v8, v9
	s_waitcnt lgkmcnt(0)
	v_cvt_pk_f16_f32 v0, v12, v13
	v_lshl_add_u64 v[6:7], v[10:11], 0, v[6:7]
	global_store_dwordx4 v[6:7], v[0:3], off sc1 nt
	s_nop 1
	ds_read2_b32 v[0:1], v214 offset0:222 offset1:255
	ds_read2_b32 v[6:7], v214 offset0:156 offset1:189
	ds_read2_b32 v[8:9], v214 offset0:90 offset1:123
	ds_read2_b32 v[12:13], v214 offset0:24 offset1:57
	v_add_u32_e32 v4, 24, v4
	v_ashrrev_i32_e32 v5, 31, v4
	v_lshlrev_b64 v[4:5], 11, v[4:5]
	s_waitcnt lgkmcnt(3)
	v_cvt_pk_f16_f32 v3, v0, v1
	s_waitcnt lgkmcnt(2)
	v_cvt_pk_f16_f32 v2, v6, v7
	s_waitcnt lgkmcnt(1)
	v_cvt_pk_f16_f32 v1, v8, v9
	s_waitcnt lgkmcnt(0)
	v_cvt_pk_f16_f32 v0, v12, v13
	v_lshl_add_u64 v[4:5], v[10:11], 0, v[4:5]
	global_store_dwordx4 v[4:5], v[0:3], off sc1 nt
	s_nop 1
	s_waitcnt lgkmcnt(0)

.LBB0_128:
	s_cmpk_gt_i32 s14, 0x1ff
	s_mov_b64 s[0:1], -1
	s_cbranch_scc0 .LBB0_158
	s_cmpk_gt_u32 s14, 0x3ff
	s_cbranch_scc0 .LBB0_155
	s_cmpk_gt_u32 s14, 0x5ff
	s_cbranch_scc0 .LBB0_152
	s_and_b32 s8, s12, 0x3e0
	s_cmpk_gt_u32 s14, 0x7ff
	v_or_b32_e32 v0, s8, v193
	s_cbranch_scc0 .LBB0_133
	s_and_b32 s0, s13, 0x7fffffc0
	s_add_i32 s4, s0, 0xfffff000
	v_readlane_b32 s52, v255, 0
	v_or_b32_e32 v30, s4, v210
	v_lshlrev_b32_e32 v194, 2, v0
	v_readlane_b32 s54, v255, 2
	v_readlane_b32 s55, v255, 3
	v_mov_b32_e32 v31, v195
	v_lshlrev_b64 v[2:3], 12, v[30:31]
	v_lshl_add_u64 v[32:33], s[54:55], 0, v[194:195]
	v_or_b32_e32 v194, 8, v30
	v_lshlrev_b64 v[4:5], 12, v[194:195]
	v_or_b32_e32 v194, 16, v30
	v_lshlrev_b64 v[10:11], 12, v[194:195]
	v_or_b32_e32 v194, 24, v30
	v_lshlrev_b64 v[12:13], 12, v[194:195]
	v_or_b32_e32 v194, 32, v30
	v_lshlrev_b64 v[18:19], 12, v[194:195]
	v_or_b32_e32 v194, 40, v30
	v_lshlrev_b64 v[20:21], 12, v[194:195]
	v_lshl_add_u64 v[2:3], v[32:33], 0, v[2:3]
	v_lshl_add_u64 v[6:7], v[32:33], 0, v[4:5]
	v_lshl_add_u64 v[10:11], v[32:33], 0, v[10:11]
	v_lshl_add_u64 v[14:15], v[32:33], 0, v[12:13]
	v_lshl_add_u64 v[18:19], v[32:33], 0, v[18:19]
	v_lshl_add_u64 v[22:23], v[32:33], 0, v[20:21]
	global_load_dwordx4 v[2:5], v[2:3], off
	s_nop 0
	global_load_dwordx4 v[6:9], v[6:7], off
	s_nop 0
	global_load_dwordx4 v[10:13], v[10:11], off
	s_nop 0
	global_load_dwordx4 v[14:17], v[14:15], off
	s_nop 0
	global_load_dwordx4 v[18:21], v[18:19], off
	s_nop 0
	global_load_dwordx4 v[22:25], v[22:23], off
	v_or_b32_e32 v194, 48, v30
	v_lshlrev_b64 v[26:27], 12, v[194:195]
	v_lshl_add_u64 v[26:27], v[32:33], 0, v[26:27]
	v_or_b32_e32 v194, 56, v30
	global_load_dwordx4 v[26:29], v[26:27], off
	v_lshlrev_b64 v[30:31], 12, v[194:195]
	v_lshl_add_u64 v[30:31], v[32:33], 0, v[30:31]
	global_load_dwordx4 v[30:33], v[30:31], off
	v_or_b32_e32 v1, s8, v210
	v_lshl_add_u64 v[34:35], s[4:5], 1, v[196:197]
	v_lshlrev_b32_e32 v194, 9, v1
	v_lshl_add_u64 v[36:37], v[34:35], 0, v[194:195]
	v_or_b32_e32 v38, s8, v211
	v_lshlrev_b32_e32 v194, 9, v38
	v_or_b32_e32 v39, s8, v212
	v_or_b32_e32 v40, s8, v213
	v_readlane_b32 s53, v255, 1
	v_readlane_b32 s56, v255, 4
	v_readlane_b32 s57, v255, 5
	v_readlane_b32 s58, v255, 6
	v_readlane_b32 s59, v255, 7
	s_mov_b64 s[0:1], 0
	s_waitcnt vmcnt(0)
	ds_write2_b32 v215, v2, v3 offset1:1
	ds_write2_b32 v215, v4, v5 offset0:2 offset1:3
	ds_write2_b32 v216, v6, v7 offset1:1
	ds_write2_b32 v217, v8, v9 offset1:1
	ds_write2_b32 v218, v10, v11 offset1:1
	ds_write2_b32 v219, v12, v13 offset1:1
	ds_write2_b32 v220, v14, v15 offset1:1
	ds_write2_b32 v221, v16, v17 offset1:1
	ds_write2_b32 v222, v18, v19 offset1:1
	ds_write2_b32 v223, v20, v21 offset1:1
	ds_write2_b32 v224, v22, v23 offset1:1
	ds_write2_b32 v225, v24, v25 offset1:1
	ds_write2_b32 v226, v26, v27 offset1:1
	ds_write2_b32 v227, v28, v29 offset1:1
	ds_write2_b32 v228, v30, v31 offset1:1
	ds_write2_b32 v229, v32, v33 offset1:1
	s_waitcnt lgkmcnt(0)
	ds_read2_b32 v[2:3], v214 offset0:198 offset1:231
	ds_read2_b32 v[6:7], v214 offset0:132 offset1:165
	ds_read2_b32 v[8:9], v214 offset0:66 offset1:99
	ds_read2_b32 v[10:11], v214 offset1:33
	v_lshl_add_u64 v[12:13], v[34:35], 0, v[194:195]
	s_waitcnt lgkmcnt(3)
	v_cvt_pk_f16_f32 v5, v2, v3
	s_waitcnt lgkmcnt(2)
	v_cvt_pk_f16_f32 v4, v6, v7
	s_waitcnt lgkmcnt(1)
	v_cvt_pk_f16_f32 v3, v8, v9
	s_waitcnt lgkmcnt(0)
	v_cvt_pk_f16_f32 v2, v10, v11
	global_store_dwordx4 v[36:37], v[2:5], off sc1 nt
	s_nop 1
	ds_read2_b32 v[2:3], v214 offset0:206 offset1:239
	ds_read2_b32 v[6:7], v214 offset0:140 offset1:173
	ds_read2_b32 v[8:9], v214 offset0:74 offset1:107
	ds_read2_b32 v[10:11], v214 offset0:8 offset1:41
	v_lshlrev_b32_e32 v194, 9, v39
	s_waitcnt lgkmcnt(3)
	v_cvt_pk_f16_f32 v5, v2, v3
	s_waitcnt lgkmcnt(2)
	v_cvt_pk_f16_f32 v4, v6, v7
	s_waitcnt lgkmcnt(1)
	v_cvt_pk_f16_f32 v3, v8, v9
	s_waitcnt lgkmcnt(0)
	v_cvt_pk_f16_f32 v2, v10, v11
	global_store_dwordx4 v[12:13], v[2:5], off sc1 nt
	s_nop 1
	ds_read2_b32 v[2:3], v214 offset0:214 offset1:247
	ds_read2_b32 v[6:7], v214 offset0:148 offset1:181
	ds_read2_b32 v[8:9], v214 offset0:82 offset1:115
	ds_read2_b32 v[10:11], v214 offset0:16 offset1:49
	v_lshl_add_u64 v[12:13], v[34:35], 0, v[194:195]
	s_waitcnt lgkmcnt(3)
	v_cvt_pk_f16_f32 v5, v2, v3
	s_waitcnt lgkmcnt(2)
	v_cvt_pk_f16_f32 v4, v6, v7
	s_waitcnt lgkmcnt(1)
	v_cvt_pk_f16_f32 v3, v8, v9
	s_waitcnt lgkmcnt(0)
	v_cvt_pk_f16_f32 v2, v10, v11
	global_store_dwordx4 v[12:13], v[2:5], off sc1 nt
	s_nop 1
	ds_read2_b32 v[2:3], v214 offset0:222 offset1:255
	ds_read2_b32 v[6:7], v214 offset0:156 offset1:189
	ds_read2_b32 v[8:9], v214 offset0:90 offset1:123
	ds_read2_b32 v[10:11], v214 offset0:24 offset1:57
	v_lshlrev_b32_e32 v194, 9, v40
	s_waitcnt lgkmcnt(3)
	v_cvt_pk_f16_f32 v5, v2, v3
	s_waitcnt lgkmcnt(2)
	v_cvt_pk_f16_f32 v4, v6, v7
	s_waitcnt lgkmcnt(1)
	v_cvt_pk_f16_f32 v3, v8, v9
	s_waitcnt lgkmcnt(0)
	v_cvt_pk_f16_f32 v2, v10, v11
	v_lshl_add_u64 v[6:7], v[34:35], 0, v[194:195]
	global_store_dwordx4 v[6:7], v[2:5], off sc1 nt
	s_nop 1
	s_waitcnt lgkmcnt(0)

.LBB0_150:
	s_waitcnt vmcnt(0)
	ds_write2_b32 v215, v0, v1 offset1:1
	ds_write2_b32 v215, v2, v3 offset0:2 offset1:3
	ds_write2_b32 v216, v4, v5 offset1:1
	ds_write2_b32 v217, v6, v7 offset1:1
	ds_write2_b32 v218, v8, v9 offset1:1
	ds_write2_b32 v219, v10, v11 offset1:1
	ds_write2_b32 v220, v12, v13 offset1:1
	ds_write2_b32 v221, v14, v15 offset1:1
	ds_write2_b32 v222, v16, v17 offset1:1
	ds_write2_b32 v223, v18, v19 offset1:1
	ds_write2_b32 v224, v20, v21 offset1:1
	ds_write2_b32 v225, v22, v23 offset1:1
	ds_write2_b32 v226, v24, v25 offset1:1
	ds_write2_b32 v227, v26, v27 offset1:1
	ds_write2_b32 v228, v28, v29 offset1:1
	ds_write2_b32 v229, v30, v31 offset1:1
	s_waitcnt lgkmcnt(0)
	ds_read2_b32 v[0:1], v214 offset0:198 offset1:231
	ds_read2_b32 v[4:5], v214 offset0:132 offset1:165
	ds_read2_b32 v[6:7], v214 offset0:66 offset1:99
	ds_read2_b32 v[8:9], v214 offset1:33
	v_lshl_add_u64 v[10:11], s[4:5], 1, v[198:199]
	s_waitcnt lgkmcnt(3)
	v_cvt_pk_f16_f32 v3, v0, v1
	s_waitcnt lgkmcnt(2)
	v_cvt_pk_f16_f32 v2, v4, v5
	v_or_b32_e32 v4, s8, v210
	v_lshlrev_b32_e32 v194, 11, v4
	s_waitcnt lgkmcnt(1)
	v_cvt_pk_f16_f32 v1, v6, v7
	s_waitcnt lgkmcnt(0)
	v_cvt_pk_f16_f32 v0, v8, v9
	v_lshl_add_u64 v[4:5], v[10:11], 0, v[194:195]
	global_store_dwordx4 v[4:5], v[0:3], off sc1 nt
	s_nop 1
	ds_read2_b32 v[0:1], v214 offset0:206 offset1:239
	ds_read2_b32 v[4:5], v214 offset0:140 offset1:173
	ds_read2_b32 v[6:7], v214 offset0:74 offset1:107
	ds_read2_b32 v[8:9], v214 offset0:8 offset1:41
	s_waitcnt lgkmcnt(3)
	v_cvt_pk_f16_f32 v3, v0, v1
	s_waitcnt lgkmcnt(2)
	v_cvt_pk_f16_f32 v2, v4, v5
	v_or_b32_e32 v4, s8, v211
	v_lshlrev_b32_e32 v194, 11, v4
	s_waitcnt lgkmcnt(1)
	v_cvt_pk_f16_f32 v1, v6, v7
	s_waitcnt lgkmcnt(0)
	v_cvt_pk_f16_f32 v0, v8, v9
	v_lshl_add_u64 v[4:5], v[10:11], 0, v[194:195]
	global_store_dwordx4 v[4:5], v[0:3], off sc1 nt
	s_nop 1
	ds_read2_b32 v[0:1], v214 offset0:214 offset1:247
	ds_read2_b32 v[4:5], v214 offset0:148 offset1:181
	ds_read2_b32 v[6:7], v214 offset0:82 offset1:115
	ds_read2_b32 v[8:9], v214 offset0:16 offset1:49
	s_waitcnt lgkmcnt(3)
	v_cvt_pk_f16_f32 v3, v0, v1
	s_waitcnt lgkmcnt(2)
	v_cvt_pk_f16_f32 v2, v4, v5
	v_or_b32_e32 v4, s8, v212
	v_lshlrev_b32_e32 v194, 11, v4
	s_waitcnt lgkmcnt(1)
	v_cvt_pk_f16_f32 v1, v6, v7
	s_waitcnt lgkmcnt(0)
	v_cvt_pk_f16_f32 v0, v8, v9
	v_lshl_add_u64 v[4:5], v[10:11], 0, v[194:195]
	global_store_dwordx4 v[4:5], v[0:3], off sc1 nt
	s_nop 1
	ds_read2_b32 v[0:1], v214 offset0:222 offset1:255
	ds_read2_b32 v[4:5], v214 offset0:156 offset1:189
	ds_read2_b32 v[6:7], v214 offset0:90 offset1:123
	ds_read2_b32 v[8:9], v214 offset0:24 offset1:57
	s_waitcnt lgkmcnt(3)
	v_cvt_pk_f16_f32 v3, v0, v1
	s_waitcnt lgkmcnt(2)
	v_cvt_pk_f16_f32 v2, v4, v5
	v_or_b32_e32 v4, s8, v213
	v_lshlrev_b32_e32 v194, 11, v4
	s_waitcnt lgkmcnt(1)
	v_cvt_pk_f16_f32 v1, v6, v7
	s_waitcnt lgkmcnt(0)
	v_cvt_pk_f16_f32 v0, v8, v9
	v_lshl_add_u64 v[4:5], v[10:11], 0, v[194:195]
	global_store_dwordx4 v[4:5], v[0:3], off sc1 nt
	s_nop 1
	s_waitcnt lgkmcnt(0)

.LBB0_152:
	s_andn2_b64 vcc, exec, s[0:1]
	s_cbranch_vccnz .LBB0_154
	s_and_b32 s0, s13, 0xfc0
	s_add_i32 s4, s0, 0xfffff800
	s_and_b32 s0, s12, 0x3e0
	v_or_b32_e32 v0, s0, v193
	v_readlane_b32 s52, v255, 14
	v_or_b32_e32 v28, s4, v210
	v_lshlrev_b32_e32 v194, 2, v0
	v_readlane_b32 s64, v255, 26
	v_readlane_b32 s65, v255, 27
	v_mov_b32_e32 v29, v195
	v_lshlrev_b64 v[0:1], 12, v[28:29]
	v_lshl_add_u64 v[30:31], s[64:65], 0, v[194:195]
	v_or_b32_e32 v194, 8, v28
	v_lshlrev_b64 v[2:3], 12, v[194:195]
	v_or_b32_e32 v194, 16, v28
	v_lshlrev_b64 v[8:9], 12, v[194:195]
	v_or_b32_e32 v194, 24, v28
	v_lshlrev_b64 v[10:11], 12, v[194:195]
	v_or_b32_e32 v194, 32, v28
	v_lshlrev_b64 v[16:17], 12, v[194:195]
	v_or_b32_e32 v194, 40, v28
	v_lshlrev_b64 v[18:19], 12, v[194:195]
	v_lshl_add_u64 v[0:1], v[30:31], 0, v[0:1]
	v_lshl_add_u64 v[4:5], v[30:31], 0, v[2:3]
	v_lshl_add_u64 v[8:9], v[30:31], 0, v[8:9]
	v_lshl_add_u64 v[12:13], v[30:31], 0, v[10:11]
	v_lshl_add_u64 v[16:17], v[30:31], 0, v[16:17]
	v_lshl_add_u64 v[20:21], v[30:31], 0, v[18:19]
	global_load_dwordx4 v[0:3], v[0:1], off
	s_nop 0
	global_load_dwordx4 v[4:7], v[4:5], off
	s_nop 0
	global_load_dwordx4 v[8:11], v[8:9], off
	s_nop 0
	global_load_dwordx4 v[12:15], v[12:13], off
	s_nop 0
	global_load_dwordx4 v[16:19], v[16:17], off
	s_nop 0
	global_load_dwordx4 v[20:23], v[20:21], off
	v_or_b32_e32 v194, 48, v28
	v_lshlrev_b64 v[24:25], 12, v[194:195]
	v_lshl_add_u64 v[24:25], v[30:31], 0, v[24:25]
	v_or_b32_e32 v194, 56, v28
	global_load_dwordx4 v[24:27], v[24:25], off
	v_lshlrev_b64 v[28:29], 12, v[194:195]
	v_lshl_add_u64 v[28:29], v[30:31], 0, v[28:29]
	global_load_dwordx4 v[28:31], v[28:29], off
	v_or_b32_e32 v34, s0, v210
	v_lshl_add_u64 v[32:33], s[4:5], 1, v[200:201]
	v_lshlrev_b32_e32 v194, 11, v34
	v_lshl_add_u64 v[34:35], v[32:33], 0, v[194:195]
	v_or_b32_e32 v36, s0, v211
	v_lshlrev_b32_e32 v194, 11, v36
	v_or_b32_e32 v37, s0, v212
	v_or_b32_e32 v38, s0, v213
	v_readlane_b32 s53, v255, 15
	v_readlane_b32 s54, v255, 16
	v_readlane_b32 s55, v255, 17
	v_readlane_b32 s56, v255, 18
	v_readlane_b32 s57, v255, 19
	v_readlane_b32 s58, v255, 20
	v_readlane_b32 s59, v255, 21
	v_readlane_b32 s60, v255, 22
	v_readlane_b32 s61, v255, 23
	v_readlane_b32 s62, v255, 24
	v_readlane_b32 s63, v255, 25
	v_readlane_b32 s66, v255, 28
	v_readlane_b32 s67, v255, 29
	s_waitcnt vmcnt(0)
	ds_write2_b32 v215, v0, v1 offset1:1
	ds_write2_b32 v215, v2, v3 offset0:2 offset1:3
	ds_write2_b32 v216, v4, v5 offset1:1
	ds_write2_b32 v217, v6, v7 offset1:1
	ds_write2_b32 v218, v8, v9 offset1:1
	ds_write2_b32 v219, v10, v11 offset1:1
	ds_write2_b32 v220, v12, v13 offset1:1
	ds_write2_b32 v221, v14, v15 offset1:1
	ds_write2_b32 v222, v16, v17 offset1:1
	ds_write2_b32 v223, v18, v19 offset1:1
	ds_write2_b32 v224, v20, v21 offset1:1
	ds_write2_b32 v225, v22, v23 offset1:1
	ds_write2_b32 v226, v24, v25 offset1:1
	ds_write2_b32 v227, v26, v27 offset1:1
	ds_write2_b32 v228, v28, v29 offset1:1
	ds_write2_b32 v229, v30, v31 offset1:1
	s_waitcnt lgkmcnt(0)
	ds_read2_b32 v[0:1], v214 offset0:198 offset1:231
	ds_read2_b32 v[4:5], v214 offset0:132 offset1:165
	ds_read2_b32 v[6:7], v214 offset0:66 offset1:99
	ds_read2_b32 v[8:9], v214 offset1:33
	v_lshl_add_u64 v[10:11], v[32:33], 0, v[194:195]
	s_waitcnt lgkmcnt(3)
	v_cvt_pk_f16_f32 v3, v0, v1
	s_waitcnt lgkmcnt(2)
	v_cvt_pk_f16_f32 v2, v4, v5
	s_waitcnt lgkmcnt(1)
	v_cvt_pk_f16_f32 v1, v6, v7
	s_waitcnt lgkmcnt(0)
	v_cvt_pk_f16_f32 v0, v8, v9
	global_store_dwordx4 v[34:35], v[0:3], off sc1 nt
	s_nop 1
	ds_read2_b32 v[0:1], v214 offset0:206 offset1:239
	ds_read2_b32 v[4:5], v214 offset0:140 offset1:173
	ds_read2_b32 v[6:7], v214 offset0:74 offset1:107
	ds_read2_b32 v[8:9], v214 offset0:8 offset1:41
	v_lshlrev_b32_e32 v194, 11, v37
	s_waitcnt lgkmcnt(3)
	v_cvt_pk_f16_f32 v3, v0, v1
	s_waitcnt lgkmcnt(2)
	v_cvt_pk_f16_f32 v2, v4, v5
	s_waitcnt lgkmcnt(1)
	v_cvt_pk_f16_f32 v1, v6, v7
	s_waitcnt lgkmcnt(0)
	v_cvt_pk_f16_f32 v0, v8, v9
	global_store_dwordx4 v[10:11], v[0:3], off sc1 nt
	s_nop 1
	ds_read2_b32 v[0:1], v214 offset0:214 offset1:247
	ds_read2_b32 v[4:5], v214 offset0:148 offset1:181
	ds_read2_b32 v[6:7], v214 offset0:82 offset1:115
	ds_read2_b32 v[8:9], v214 offset0:16 offset1:49
	v_lshl_add_u64 v[10:11], v[32:33], 0, v[194:195]
	s_waitcnt lgkmcnt(3)
	v_cvt_pk_f16_f32 v3, v0, v1
	s_waitcnt lgkmcnt(2)
	v_cvt_pk_f16_f32 v2, v4, v5
	s_waitcnt lgkmcnt(1)
	v_cvt_pk_f16_f32 v1, v6, v7
	s_waitcnt lgkmcnt(0)
	v_cvt_pk_f16_f32 v0, v8, v9
	global_store_dwordx4 v[10:11], v[0:3], off sc1 nt
	s_nop 1
	ds_read2_b32 v[0:1], v214 offset0:222 offset1:255
	ds_read2_b32 v[4:5], v214 offset0:156 offset1:189
	ds_read2_b32 v[6:7], v214 offset0:90 offset1:123
	ds_read2_b32 v[8:9], v214 offset0:24 offset1:57
	v_lshlrev_b32_e32 v194, 11, v38
	s_waitcnt lgkmcnt(3)
	v_cvt_pk_f16_f32 v3, v0, v1
	s_waitcnt lgkmcnt(2)
	v_cvt_pk_f16_f32 v2, v4, v5
	s_waitcnt lgkmcnt(1)
	v_cvt_pk_f16_f32 v1, v6, v7
	s_waitcnt lgkmcnt(0)
	v_cvt_pk_f16_f32 v0, v8, v9
	v_lshl_add_u64 v[4:5], v[32:33], 0, v[194:195]
	global_store_dwordx4 v[4:5], v[0:3], off sc1 nt
	s_nop 1
	s_waitcnt lgkmcnt(0)

.LBB0_155:
	s_andn2_b64 vcc, exec, s[0:1]
	s_cbranch_vccnz .LBB0_157
	s_and_b32 s0, s13, 0x7c0
	s_add_i32 s4, s0, 0xfffffc00
	s_and_b32 s0, s12, 0x3e0
	v_or_b32_e32 v0, s0, v193
	v_readlane_b32 s52, v255, 14
	v_or_b32_e32 v28, s4, v210
	v_lshlrev_b32_e32 v194, 2, v0
	v_readlane_b32 s62, v255, 24
	v_readlane_b32 s63, v255, 25
	v_mov_b32_e32 v29, v195
	v_lshlrev_b64 v[0:1], 12, v[28:29]
	v_lshl_add_u64 v[30:31], s[62:63], 0, v[194:195]
	v_or_b32_e32 v194, 8, v28
	v_lshlrev_b64 v[2:3], 12, v[194:195]
	v_or_b32_e32 v194, 16, v28
	v_lshlrev_b64 v[8:9], 12, v[194:195]
	v_or_b32_e32 v194, 24, v28
	v_lshlrev_b64 v[10:11], 12, v[194:195]
	v_or_b32_e32 v194, 32, v28
	v_lshlrev_b64 v[16:17], 12, v[194:195]
	v_or_b32_e32 v194, 40, v28
	v_lshlrev_b64 v[18:19], 12, v[194:195]
	v_lshl_add_u64 v[0:1], v[30:31], 0, v[0:1]
	v_lshl_add_u64 v[4:5], v[30:31], 0, v[2:3]
	v_lshl_add_u64 v[8:9], v[30:31], 0, v[8:9]
	v_lshl_add_u64 v[12:13], v[30:31], 0, v[10:11]
	v_lshl_add_u64 v[16:17], v[30:31], 0, v[16:17]
	v_lshl_add_u64 v[20:21], v[30:31], 0, v[18:19]
	global_load_dwordx4 v[0:3], v[0:1], off
	s_nop 0
	global_load_dwordx4 v[4:7], v[4:5], off
	s_nop 0
	global_load_dwordx4 v[8:11], v[8:9], off
	s_nop 0
	global_load_dwordx4 v[12:15], v[12:13], off
	s_nop 0
	global_load_dwordx4 v[16:19], v[16:17], off
	s_nop 0
	global_load_dwordx4 v[20:23], v[20:21], off
	v_or_b32_e32 v194, 48, v28
	v_lshlrev_b64 v[24:25], 12, v[194:195]
	v_lshl_add_u64 v[24:25], v[30:31], 0, v[24:25]
	v_or_b32_e32 v194, 56, v28
	global_load_dwordx4 v[24:27], v[24:25], off
	v_lshlrev_b64 v[28:29], 12, v[194:195]
	v_lshl_add_u64 v[28:29], v[30:31], 0, v[28:29]
	global_load_dwordx4 v[28:31], v[28:29], off
	v_or_b32_e32 v34, s0, v210
	v_lshl_add_u64 v[32:33], s[4:5], 1, v[202:203]
	v_lshlrev_b32_e32 v194, 11, v34
	v_lshl_add_u64 v[34:35], v[32:33], 0, v[194:195]
	v_or_b32_e32 v36, s0, v211
	v_lshlrev_b32_e32 v194, 11, v36
	v_or_b32_e32 v37, s0, v212
	v_or_b32_e32 v38, s0, v213
	v_readlane_b32 s53, v255, 15
	v_readlane_b32 s54, v255, 16
	v_readlane_b32 s55, v255, 17
	v_readlane_b32 s56, v255, 18
	v_readlane_b32 s57, v255, 19
	v_readlane_b32 s58, v255, 20
	v_readlane_b32 s59, v255, 21
	v_readlane_b32 s60, v255, 22
	v_readlane_b32 s61, v255, 23
	v_readlane_b32 s64, v255, 26
	v_readlane_b32 s65, v255, 27
	v_readlane_b32 s66, v255, 28
	v_readlane_b32 s67, v255, 29
	s_waitcnt vmcnt(0)
	ds_write2_b32 v215, v0, v1 offset1:1
	ds_write2_b32 v215, v2, v3 offset0:2 offset1:3
	ds_write2_b32 v216, v4, v5 offset1:1
	ds_write2_b32 v217, v6, v7 offset1:1
	ds_write2_b32 v218, v8, v9 offset1:1
	ds_write2_b32 v219, v10, v11 offset1:1
	ds_write2_b32 v220, v12, v13 offset1:1
	ds_write2_b32 v221, v14, v15 offset1:1
	ds_write2_b32 v222, v16, v17 offset1:1
	ds_write2_b32 v223, v18, v19 offset1:1
	ds_write2_b32 v224, v20, v21 offset1:1
	ds_write2_b32 v225, v22, v23 offset1:1
	ds_write2_b32 v226, v24, v25 offset1:1
	ds_write2_b32 v227, v26, v27 offset1:1
	ds_write2_b32 v228, v28, v29 offset1:1
	ds_write2_b32 v229, v30, v31 offset1:1
	s_waitcnt lgkmcnt(0)
	ds_read2_b32 v[0:1], v214 offset0:198 offset1:231
	ds_read2_b32 v[4:5], v214 offset0:132 offset1:165
	ds_read2_b32 v[6:7], v214 offset0:66 offset1:99
	ds_read2_b32 v[8:9], v214 offset1:33
	v_lshl_add_u64 v[10:11], v[32:33], 0, v[194:195]
	s_waitcnt lgkmcnt(3)
	v_cvt_pk_f16_f32 v3, v0, v1
	s_waitcnt lgkmcnt(2)
	v_cvt_pk_f16_f32 v2, v4, v5
	s_waitcnt lgkmcnt(1)
	v_cvt_pk_f16_f32 v1, v6, v7
	s_waitcnt lgkmcnt(0)
	v_cvt_pk_f16_f32 v0, v8, v9
	global_store_dwordx4 v[34:35], v[0:3], off sc1 nt
	s_nop 1
	ds_read2_b32 v[0:1], v214 offset0:206 offset1:239
	ds_read2_b32 v[4:5], v214 offset0:140 offset1:173
	ds_read2_b32 v[6:7], v214 offset0:74 offset1:107
	ds_read2_b32 v[8:9], v214 offset0:8 offset1:41
	v_lshlrev_b32_e32 v194, 11, v37
	s_waitcnt lgkmcnt(3)
	v_cvt_pk_f16_f32 v3, v0, v1
	s_waitcnt lgkmcnt(2)
	v_cvt_pk_f16_f32 v2, v4, v5
	s_waitcnt lgkmcnt(1)
	v_cvt_pk_f16_f32 v1, v6, v7
	s_waitcnt lgkmcnt(0)
	v_cvt_pk_f16_f32 v0, v8, v9
	global_store_dwordx4 v[10:11], v[0:3], off sc1 nt
	s_nop 1
	ds_read2_b32 v[0:1], v214 offset0:214 offset1:247
	ds_read2_b32 v[4:5], v214 offset0:148 offset1:181
	ds_read2_b32 v[6:7], v214 offset0:82 offset1:115
	ds_read2_b32 v[8:9], v214 offset0:16 offset1:49
	v_lshl_add_u64 v[10:11], v[32:33], 0, v[194:195]
	s_waitcnt lgkmcnt(3)
	v_cvt_pk_f16_f32 v3, v0, v1
	s_waitcnt lgkmcnt(2)
	v_cvt_pk_f16_f32 v2, v4, v5
	s_waitcnt lgkmcnt(1)
	v_cvt_pk_f16_f32 v1, v6, v7
	s_waitcnt lgkmcnt(0)
	v_cvt_pk_f16_f32 v0, v8, v9
	global_store_dwordx4 v[10:11], v[0:3], off sc1 nt
	s_nop 1
	ds_read2_b32 v[0:1], v214 offset0:222 offset1:255
	ds_read2_b32 v[4:5], v214 offset0:156 offset1:189
	ds_read2_b32 v[6:7], v214 offset0:90 offset1:123
	ds_read2_b32 v[8:9], v214 offset0:24 offset1:57
	v_lshlrev_b32_e32 v194, 11, v38
	s_waitcnt lgkmcnt(3)
	v_cvt_pk_f16_f32 v3, v0, v1
	s_waitcnt lgkmcnt(2)
	v_cvt_pk_f16_f32 v2, v4, v5
	s_waitcnt lgkmcnt(1)
	v_cvt_pk_f16_f32 v1, v6, v7
	s_waitcnt lgkmcnt(0)
	v_cvt_pk_f16_f32 v0, v8, v9
	v_lshl_add_u64 v[4:5], v[32:33], 0, v[194:195]
	global_store_dwordx4 v[4:5], v[0:3], off sc1 nt
	s_nop 1
	s_waitcnt lgkmcnt(0)
